# P5 fused epilogue: final-norm gain loads issued before the row-sum exchange
# baseline (speedup 1.0000x reference)
;     __device__ __forceinline__ void fused(f32x4 (&acc)[2][2][4][2], const Unit& u, int wr, int wc, int fr, int fq, PG8_LAS unsigned char* lds, int wid, int lane) const {
;     ...
;         asm volatile("s_waitcnt lgkmcnt(0)" ::: "memory"); __builtin_amdgcn_s_barrier(); asm volatile("" ::: "memory");
;         const int row = wid * 32 + (lane & 31);
;         unsigned* slotu = (unsigned*)(xbuf + (size_t)(u.pm * BM + row) * 8);
;         if (lane < 32) { const float t = (P[row * 4 + 0] + P[row * 4 + 1]) + (P[row * 4 + 2] + P[row * 4 + 3]);
;             __hip_atomic_store(slotu + u.pn, __float_as_uint(t) | 1u, __ATOMIC_RELAXED, __HIP_MEMORY_SCOPE_AGENT); }
;         bool dead = false;
;         { const unsigned long long t0 = __builtin_amdgcn_s_memrealtime(); float q = 0.f;
;           for (;;) { bool ok = true; q = 0.f;
;             if (lane < 32) {
; #pragma unroll
;               for (int t = 0; t < 8; ++t) { const unsigned v_ = __hip_atomic_load(slotu + t, __ATOMIC_RELAXED, __HIP_MEMORY_SCOPE_AGENT); ok = ok && (v_ != 0u); q += __uint_as_float(v_); } }
;             if (__all(ok)) break;
;             if (__builtin_amdgcn_s_memrealtime() - t0 > 2000000ull) { if (lane == 0) __hip_atomic_store(tmo, 1u, __ATOMIC_RELAXED, __HIP_MEMORY_SCOPE_AGENT); dead = true; break; }
;             __builtin_amdgcn_s_sleep(2); }
;           if (lane < 32) S[row] = dead ? __builtin_nanf("") : __builtin_amdgcn_rsqf(q * (1.0f / 2048.0f) + 1e-5f); }
;         asm volatile("s_waitcnt lgkmcnt(0)" ::: "memory"); __builtin_amdgcn_s_barrier(); asm volatile("" ::: "memory");
;         const bool bad = false;
;         f32x4 gv[2][2];
; #pragma unroll
;         for (int bj = 0; bj < 2; ++bj)
; #pragma unroll
;             for (int n = 0; n < 2; ++n) gv[bj][n] = *(const f32x4*)(gfin + col0 + bj * HALF + n * 16);
.LBB0_1050:
	s_or_b64 exec, exec, s[2:3]
	v_lshlrev_b32_e32 v234, 2, v160
	global_load_dwordx4 v[218:221], v234, s[66:67]
	global_load_dwordx4 v[222:225], v234, s[66:67] offset:64
	global_load_dwordx4 v[226:229], v234, s[66:67] offset:512
	global_load_dwordx4 v[230:233], v234, s[66:67] offset:576
	v_and_b32_e32 v0, 31, v0
	v_lshl_or_b32 v4, s17, 5, v0
	v_add_u32_e32 v0, s0, v4
	v_ashrrev_i32_e32 v1, 31, v0
	s_waitcnt lgkmcnt(0)
	s_barrier
	v_lshlrev_b64 v[0:1], 5, v[0:1]
	v_lshl_add_u64 v[0:1], s[70:71], 0, v[0:1]
	s_mov_b64 s[0:1], 0xe0a0000
	v_lshl_add_u64 v[0:1], v[0:1], 0, s[0:1]
	v_cmp_gt_u32_e64 s[0:1], 32, v194
	s_and_saveexec_b64 s[2:3], s[0:1]
	s_cbranch_execz .LBB0_1052
	s_waitcnt lgkmcnt(0)
	v_lshl_add_u32 v2, v4, 4, 0
	ds_read_b128 v[6:9], v2
	s_mov_b32 s5, 0
	s_lshl_b32 s4, s16, 2
	s_waitcnt lgkmcnt(0)
	v_mov_b32_e32 v2, v7
	v_mov_b32_e32 v3, v8
	v_mov_b32_e32 v7, v9
	v_pk_add_f32 v[2:3], v[2:3], v[6:7]
	v_lshl_add_u64 v[6:7], v[0:1], 0, s[4:5]
	v_pk_add_f32 v[2:3], v[2:3], v[2:3] op_sel:[0,1] op_sel_hi:[1,0]
	s_nop 0
	v_or_b32_e32 v2, 1, v2
	global_store_dword v[6:7], v2, off sc1

;     __device__ __forceinline__ void fused(f32x4 (&acc)[2][2][4][2], const Unit& u, int wr, int wc, int fr, int fq, PG8_LAS unsigned char* lds, int wid, int lane) const {
;     ...
;         f32x4 gv[2][2];
; #pragma unroll
;         for (int bj = 0; bj < 2; ++bj)
; #pragma unroll
;             for (int n = 0; n < 2; ++n) gv[bj][n] = *(const f32x4*)(gfin + col0 + bj * HALF + n * 16);
;         const float qnan = __builtin_nanf("");
; #pragma unroll
;         for (int ai = 0; ai < 2; ++ai)
; #pragma unroll
;             for (int m = 0; m < 4; ++m) { const int r = ai * HALF + wr * 64 + m * 16 + fr; const float sr = bad ? qnan : S[r]; const size_t off = (size_t)(u.pm * BM + r) * 2048 + col0;
; #pragma unroll
;                 for (int bj = 0; bj < 2; ++bj)
; #pragma unroll
;                     for (int n = 0; n < 2; ++n) { const f32x4 a_ = acc[ai][bj][m][n], g_ = gv[bj][n]; const f32x2 sp_ = {sr, sr}, al_ = {a_[0], a_[1]}, ah_ = {a_[2], a_[3]}, gl_ = {g_[0], g_[1]}, gh_ = {g_[2], g_[3]};
;                         const f32x2 yl_ = (al_ * sp_) * gl_, yh_ = (ah_ * sp_) * gh_;
;                         *(f32x4*)(out + off + bj * HALF + n * 16) = (f32x4){yl_[0], yl_[1], yh_[0], yh_[1]}; } }
.LBB0_1065:
	s_or_b64 exec, exec, s[2:3]
	s_waitcnt lgkmcnt(0)
	s_barrier
	v_lshlrev_b32_e32 v160, 2, v160
	s_waitcnt vmcnt(0)
	v_mov_b64_e32 v[12:13], v[218:219]
	v_mov_b64_e32 v[14:15], v[220:221]
	v_mov_b64_e32 v[8:9], v[222:223]
	v_mov_b64_e32 v[10:11], v[224:225]
	v_mov_b64_e32 v[4:5], v[226:227]
	v_mov_b64_e32 v[6:7], v[228:229]
	v_mov_b64_e32 v[0:1], v[230:231]
	v_mov_b64_e32 v[2:3], v[232:233]
	v_lshl_add_u32 v162, v162, 2, 0
	v_add_u32_e32 v186, 0x1000, v162
	ds_read2_b32 v[162:163], v186 offset1:16
	ds_read2_b32 v[166:167], v186 offset0:32 offset1:48
	v_lshlrev_b64 v[130:131], 13, v[130:131]
	v_mov_b32_e32 v161, 0
	v_lshl_add_u64 v[130:131], s[68:69], 0, v[130:131]
	v_lshlrev_b64 v[132:133], 13, v[132:133]
	v_lshlrev_b64 v[134:135], 13, v[134:135]
	v_lshl_add_u64 v[164:165], v[130:131], 0, v[160:161]
	s_waitcnt lgkmcnt(1)
	v_pk_mul_f32 v[126:127], v[126:127], v[162:163] op_sel_hi:[1,0]
	v_pk_mul_f32 v[128:129], v[128:129], v[162:163] op_sel_hi:[1,0]
	v_mov_b32_e32 v130, v163
	v_lshl_add_u64 v[132:133], s[68:69], 0, v[132:133]
	v_lshl_add_u64 v[134:135], s[68:69], 0, v[134:135]
	v_pk_mul_f32 v[122:123], v[122:123], v[162:163] op_sel_hi:[1,0]
	v_pk_mul_f32 v[124:125], v[124:125], v[162:163] op_sel_hi:[1,0]
	v_pk_mul_f32 v[118:119], v[118:119], v[162:163] op_sel_hi:[1,0]
	v_pk_mul_f32 v[120:121], v[120:121], v[162:163] op_sel_hi:[1,0]
	v_pk_mul_f32 v[114:115], v[114:115], v[162:163] op_sel_hi:[1,0]
	v_pk_mul_f32 v[116:117], v[116:117], v[162:163] op_sel_hi:[1,0]
	s_waitcnt lgkmcnt(0)
	v_pk_mul_f32 v[136:137], v[136:137], v[166:167] op_sel_hi:[1,0]
	v_pk_mul_f32 v[162:163], v[96:97], v[166:167] op_sel_hi:[1,0]
	v_pk_mul_f32 v[168:169], v[94:95], v[166:167] op_sel_hi:[1,0]
	v_pk_mul_f32 v[170:171], v[92:93], v[166:167] op_sel_hi:[1,0]
	v_pk_mul_f32 v[172:173], v[90:91], v[166:167] op_sel_hi:[1,0]
	v_pk_mul_f32 v[174:175], v[88:89], v[166:167] op_sel_hi:[1,0]
	v_pk_mul_f32 v[176:177], v[86:87], v[166:167] op_sel_hi:[1,0]
	v_pk_mul_f32 v[178:179], v[84:85], v[166:167] op_sel_hi:[1,0]
	v_pk_mul_f32 v[110:111], v[110:111], v[130:131] op_sel_hi:[1,0]
	v_pk_mul_f32 v[112:113], v[112:113], v[130:131] op_sel_hi:[1,0]
	v_pk_mul_f32 v[180:181], v[106:107], v[130:131] op_sel_hi:[1,0]
	v_pk_mul_f32 v[106:107], v[108:109], v[130:131] op_sel_hi:[1,0]
	v_pk_mul_f32 v[108:109], v[102:103], v[130:131] op_sel_hi:[1,0]
	v_pk_mul_f32 v[182:183], v[104:105], v[130:131] op_sel_hi:[1,0]
	v_pk_mul_f32 v[184:185], v[98:99], v[130:131] op_sel_hi:[1,0]
	v_pk_mul_f32 v[130:131], v[100:101], v[130:131] op_sel_hi:[1,0]
	v_lshl_add_u64 v[132:133], v[132:133], 0, v[160:161]
	v_lshl_add_u64 v[134:135], v[134:135], 0, v[160:161]
	v_lshlrev_b64 v[82:83], 13, v[82:83]
	v_lshl_add_u64 v[82:83], s[68:69], 0, v[82:83]
	v_lshl_add_u64 v[82:83], v[82:83], 0, v[160:161]
	s_waitcnt vmcnt(3)
	v_pk_mul_f32 v[86:87], v[14:15], v[128:129]
	v_pk_mul_f32 v[84:85], v[12:13], v[126:127]
	s_waitcnt vmcnt(2)
	v_pk_mul_f32 v[90:91], v[10:11], v[124:125]
	v_pk_mul_f32 v[88:89], v[8:9], v[122:123]
	s_waitcnt vmcnt(1)
	v_pk_mul_f32 v[94:95], v[6:7], v[120:121]
	v_pk_mul_f32 v[92:93], v[4:5], v[118:119]
	s_waitcnt vmcnt(0)
	v_pk_mul_f32 v[98:99], v[2:3], v[116:117]
	v_pk_mul_f32 v[96:97], v[0:1], v[114:115]
	v_pk_mul_f32 v[102:103], v[14:15], v[112:113]
	v_pk_mul_f32 v[100:101], v[12:13], v[110:111]
	v_pk_mul_f32 v[106:107], v[10:11], v[106:107]
	v_pk_mul_f32 v[104:105], v[8:9], v[180:181]
	v_pk_mul_f32 v[110:111], v[6:7], v[182:183]
	v_pk_mul_f32 v[108:109], v[4:5], v[108:109]
	v_pk_mul_f32 v[114:115], v[2:3], v[130:131]
	v_pk_mul_f32 v[112:113], v[0:1], v[184:185]
	v_pk_mul_f32 v[118:119], v[14:15], v[162:163]
	v_pk_mul_f32 v[116:117], v[12:13], v[136:137]
	v_pk_mul_f32 v[122:123], v[10:11], v[170:171]
	v_pk_mul_f32 v[120:121], v[8:9], v[168:169]
	v_pk_mul_f32 v[126:127], v[6:7], v[174:175]
	v_pk_mul_f32 v[124:125], v[4:5], v[172:173]
	v_pk_mul_f32 v[130:131], v[2:3], v[178:179]
	v_pk_mul_f32 v[128:129], v[0:1], v[176:177]
	global_store_dwordx4 v[164:165], v[84:87], off
	global_store_dwordx4 v[164:165], v[88:91], off offset:64
	global_store_dwordx4 v[164:165], v[92:95], off offset:512
	global_store_dwordx4 v[164:165], v[96:99], off offset:576
	global_store_dwordx4 v[132:133], v[100:103], off
	global_store_dwordx4 v[132:133], v[104:107], off offset:64
	global_store_dwordx4 v[132:133], v[108:111], off offset:512
	global_store_dwordx4 v[132:133], v[112:115], off offset:576
	global_store_dwordx4 v[134:135], v[116:119], off
	global_store_dwordx4 v[134:135], v[120:123], off offset:64
	global_store_dwordx4 v[134:135], v[124:127], off offset:512
	global_store_dwordx4 v[134:135], v[128:131], off offset:576
	v_mov_b32_e32 v84, v167
	v_pk_mul_f32 v[70:71], v[70:71], v[84:85] op_sel_hi:[1,0]
	v_pk_mul_f32 v[72:73], v[72:73], v[84:85] op_sel_hi:[1,0]
	v_pk_mul_f32 v[70:71], v[4:5], v[70:71]
	v_pk_mul_f32 v[72:73], v[6:7], v[72:73]
	global_store_dwordx4 v[82:83], v[70:73], off offset:512
	ds_read2_b32 v[70:71], v186 offset0:128 offset1:144
	v_pk_mul_f32 v[66:67], v[66:67], v[84:85] op_sel_hi:[1,0]
	v_pk_mul_f32 v[68:69], v[68:69], v[84:85] op_sel_hi:[1,0]
	v_pk_mul_f32 v[66:67], v[0:1], v[66:67]
	v_pk_mul_f32 v[68:69], v[2:3], v[68:69]
	global_store_dwordx4 v[82:83], v[66:69], off offset:576
	s_waitcnt lgkmcnt(0)
;     __device__ __forceinline__ void fused(f32x4 (&acc)[2][2][4][2], const Unit& u, int wr, int wc, int fr, int fq, PG8_LAS unsigned char* lds, int wid, int lane) const {
;     ...
; #pragma unroll
;         for (int ai = 0; ai < 2; ++ai)
; #pragma unroll
;             for (int m = 0; m < 4; ++m) { const int r = ai * HALF + wr * 64 + m * 16 + fr; const float sr = bad ? qnan : S[r]; const size_t off = (size_t)(u.pm * BM + r) * 2048 + col0;
; #pragma unroll
;                 for (int bj = 0; bj < 2; ++bj)
; #pragma unroll
;                     for (int n = 0; n < 2; ++n) { const f32x4 a_ = acc[ai][bj][m][n], g_ = gv[bj][n]; const f32x2 sp_ = {sr, sr}, al_ = {a_[0], a_[1]}, ah_ = {a_[2], a_[3]}, gl_ = {g_[0], g_[1]}, gh_ = {g_[2], g_[3]};
;                         const f32x2 yl_ = (al_ * sp_) * gl_, yh_ = (ah_ * sp_) * gh_;
;                         *(f32x4*)(out + off + bj * HALF + n * 16) = (f32x4){yl_[0], yl_[1], yh_[0], yh_[1]}; } }
	v_pk_mul_f32 v[50:51], v[50:51], v[70:71] op_sel_hi:[1,0]
	v_pk_mul_f32 v[52:53], v[52:53], v[70:71] op_sel_hi:[1,0]
	v_lshlrev_b64 v[66:67], 13, v[138:139]
	v_lshl_add_u64 v[66:67], s[68:69], 0, v[66:67]
	v_lshl_add_u64 v[66:67], v[66:67], 0, v[160:161]
	v_pk_mul_f32 v[52:53], v[2:3], v[52:53]
	v_pk_mul_f32 v[50:51], v[0:1], v[50:51]
	global_store_dwordx4 v[66:67], v[50:53], off offset:576
	v_pk_mul_f32 v[78:79], v[78:79], v[84:85] op_sel_hi:[1,0]
	v_pk_mul_f32 v[80:81], v[80:81], v[84:85] op_sel_hi:[1,0]
	v_lshlrev_b64 v[50:51], 13, v[142:143]
	v_mov_b32_e32 v52, v71
	v_lshl_add_u64 v[50:51], s[68:69], 0, v[50:51]
	v_pk_mul_f32 v[38:39], v[38:39], v[52:53] op_sel_hi:[1,0]
	v_pk_mul_f32 v[40:41], v[40:41], v[52:53] op_sel_hi:[1,0]
	v_lshl_add_u64 v[50:51], v[50:51], 0, v[160:161]
	v_pk_mul_f32 v[40:41], v[6:7], v[40:41]
	v_pk_mul_f32 v[38:39], v[4:5], v[38:39]
	global_store_dwordx4 v[50:51], v[38:41], off offset:512
	ds_read2_b32 v[38:39], v186 offset0:160 offset1:176
	v_pk_mul_f32 v[34:35], v[34:35], v[52:53] op_sel_hi:[1,0]
	v_pk_mul_f32 v[36:37], v[36:37], v[52:53] op_sel_hi:[1,0]
	v_pk_mul_f32 v[34:35], v[0:1], v[34:35]
	v_pk_mul_f32 v[36:37], v[2:3], v[36:37]
	global_store_dwordx4 v[50:51], v[34:37], off offset:576
	s_waitcnt lgkmcnt(0)
	v_pk_mul_f32 v[18:19], v[18:19], v[38:39] op_sel_hi:[1,0]
	v_pk_mul_f32 v[20:21], v[20:21], v[38:39] op_sel_hi:[1,0]
	v_lshlrev_b64 v[34:35], 13, v[144:145]
	v_lshl_add_u64 v[34:35], s[68:69], 0, v[34:35]
	v_lshl_add_u64 v[34:35], v[34:35], 0, v[160:161]
	v_pk_mul_f32 v[22:23], v[22:23], v[38:39] op_sel_hi:[1,0]
	v_pk_mul_f32 v[24:25], v[24:25], v[38:39] op_sel_hi:[1,0]
	v_pk_mul_f32 v[20:21], v[2:3], v[20:21]
	v_pk_mul_f32 v[18:19], v[0:1], v[18:19]
	v_pk_mul_f32 v[24:25], v[6:7], v[24:25]
	v_pk_mul_f32 v[22:23], v[4:5], v[22:23]
	global_store_dwordx4 v[34:35], v[18:21], off offset:576
	v_pk_mul_f32 v[62:63], v[62:63], v[70:71] op_sel_hi:[1,0]
	v_pk_mul_f32 v[64:65], v[64:65], v[70:71] op_sel_hi:[1,0]
	v_lshlrev_b64 v[18:19], 13, v[146:147]
	v_mov_b32_e32 v20, v39
	v_pk_mul_f32 v[46:47], v[46:47], v[52:53] op_sel_hi:[1,0]
	v_pk_mul_f32 v[48:49], v[48:49], v[52:53] op_sel_hi:[1,0]
	v_pk_mul_f32 v[30:31], v[30:31], v[38:39] op_sel_hi:[1,0]
	v_pk_mul_f32 v[32:33], v[32:33], v[38:39] op_sel_hi:[1,0]
	global_store_dwordx4 v[34:35], v[22:25], off offset:512
	v_lshl_add_u64 v[18:19], s[68:69], 0, v[18:19]
	v_pk_mul_f32 v[80:81], v[14:15], v[80:81]
	v_pk_mul_f32 v[22:23], v[158:159], v[20:21] op_sel_hi:[1,0]
	v_pk_mul_f32 v[24:25], v[156:157], v[20:21] op_sel_hi:[1,0]
	v_pk_mul_f32 v[78:79], v[12:13], v[78:79]
	v_pk_mul_f32 v[64:65], v[14:15], v[64:65]
	v_pk_mul_f32 v[62:63], v[12:13], v[62:63]
	v_pk_mul_f32 v[48:49], v[14:15], v[48:49]
	v_pk_mul_f32 v[46:47], v[12:13], v[46:47]
	v_pk_mul_f32 v[32:33], v[14:15], v[32:33]
	v_pk_mul_f32 v[30:31], v[12:13], v[30:31]
	v_pk_mul_f32 v[14:15], v[14:15], v[24:25]
	v_pk_mul_f32 v[12:13], v[12:13], v[22:23]
	v_lshl_add_u64 v[18:19], v[18:19], 0, v[160:161]
	global_store_dwordx4 v[82:83], v[78:81], off
	v_pk_mul_f32 v[74:75], v[74:75], v[84:85] op_sel_hi:[1,0]
	v_pk_mul_f32 v[76:77], v[76:77], v[84:85] op_sel_hi:[1,0]
	v_pk_mul_f32 v[58:59], v[58:59], v[70:71] op_sel_hi:[1,0]
	v_pk_mul_f32 v[60:61], v[60:61], v[70:71] op_sel_hi:[1,0]
	v_pk_mul_f32 v[42:43], v[42:43], v[52:53] op_sel_hi:[1,0]
	v_pk_mul_f32 v[44:45], v[44:45], v[52:53] op_sel_hi:[1,0]
	v_pk_mul_f32 v[26:27], v[26:27], v[38:39] op_sel_hi:[1,0]
	v_pk_mul_f32 v[28:29], v[28:29], v[38:39] op_sel_hi:[1,0]
	global_store_dwordx4 v[18:19], v[12:15], off
	v_pk_mul_f32 v[76:77], v[10:11], v[76:77]
	v_pk_mul_f32 v[74:75], v[8:9], v[74:75]
	v_pk_mul_f32 v[12:13], v[154:155], v[20:21] op_sel_hi:[1,0]
	v_pk_mul_f32 v[14:15], v[152:153], v[20:21] op_sel_hi:[1,0]
	v_pk_mul_f32 v[60:61], v[10:11], v[60:61]
	v_pk_mul_f32 v[58:59], v[8:9], v[58:59]
	v_pk_mul_f32 v[44:45], v[10:11], v[44:45]
	v_pk_mul_f32 v[42:43], v[8:9], v[42:43]
	v_pk_mul_f32 v[28:29], v[10:11], v[28:29]
	v_pk_mul_f32 v[26:27], v[8:9], v[26:27]
	v_pk_mul_f32 v[10:11], v[10:11], v[14:15]
	v_pk_mul_f32 v[8:9], v[8:9], v[12:13]
	global_store_dwordx4 v[82:83], v[74:77], off offset:64
	v_pk_mul_f32 v[54:55], v[54:55], v[70:71] op_sel_hi:[1,0]
	v_pk_mul_f32 v[56:57], v[56:57], v[70:71] op_sel_hi:[1,0]
	global_store_dwordx4 v[18:19], v[8:11], off offset:64
	v_pk_mul_f32 v[56:57], v[6:7], v[56:57]
	v_pk_mul_f32 v[54:55], v[4:5], v[54:55]
	v_pk_mul_f32 v[8:9], v[150:151], v[20:21] op_sel_hi:[1,0]
	v_pk_mul_f32 v[10:11], v[140:141], v[20:21] op_sel_hi:[1,0]
	v_pk_mul_f32 v[4:5], v[4:5], v[8:9]
	v_pk_mul_f32 v[6:7], v[6:7], v[10:11]
	global_store_dwordx4 v[18:19], v[4:7], off offset:512
	global_store_dwordx4 v[66:67], v[62:65], off
	global_store_dwordx4 v[66:67], v[58:61], off offset:64
	v_pk_mul_f32 v[4:5], v[148:149], v[20:21] op_sel_hi:[1,0]
	v_pk_mul_f32 v[6:7], v[16:17], v[20:21] op_sel_hi:[1,0]
	v_pk_mul_f32 v[0:1], v[0:1], v[4:5]
	v_pk_mul_f32 v[2:3], v[2:3], v[6:7]
	global_store_dwordx4 v[66:67], v[54:57], off offset:512
	global_store_dwordx4 v[50:51], v[46:49], off
	global_store_dwordx4 v[50:51], v[42:45], off offset:64
	global_store_dwordx4 v[34:35], v[30:33], off
	global_store_dwordx4 v[34:35], v[26:29], off offset:64
	global_store_dwordx4 v[18:19], v[0:3], off offset:576
